# HGRN unit: log-forget loads two chunks ahead into landing registers, cumulative sums recomputed in the preparation (no stored copy), deep LDS operand prefetch in the MFMA part
# speedup vs baseline: 1.0009x; 1.0009x over previous
.LBB0_583:
	s_and_b64 vcc, exec, s[0:1]
	s_cbranch_vccz .LBB0_747
	v_readlane_b32 s0, v244, 0
	v_readlane_b32 s1, v244, 1
	s_mov_b64 s[6:7], s[46:47]
	v_mov_b32_e32 v58, v194
	s_andn2_b64 vcc, exec, s[0:1]
	s_cbranch_vccnz .LBB0_610
	s_mov_b32 s29, 0x428c0000
	s_mov_b32 s20, 0x05040100
	s_and_b32 s0, s2, 3
	s_lshr_b32 s1, s2, 2
	s_mul_i32 s16, s1, 43
	s_lshr_b32 s16, s16, 8
	s_mul_i32 s17, s16, 6
	s_sub_u32 s17, s1, s17
	s_lshl_b32 s16, s16, 12
	s_lshl_b32 s0, s0, 10
	s_add_u32 s16, s16, s0
	s_lshl_b32 s17, s17, 7
	s_mul_i32 s0, s16, 0x300
	s_add_u32 s0, s0, s17
	s_lshl_b32 s1, s0, 2
	s_add_u32 s4, s6, s1
	s_addc_u32 s5, s7, 0
	s_add_u32 s4, s4, 0x16200000
	s_addc_u32 s5, s5, 0
	s_lshl_b32 s1, s0, 1
	s_add_u32 s8, s6, s1
	s_addc_u32 s9, s7, 0
	s_add_u32 s10, s8, 0x10200000
	s_addc_u32 s11, s9, 0
	s_add_u32 s8, s8, 0xd200000
	s_addc_u32 s9, s9, 0
	s_add_u32 s12, s44, s1
	s_addc_u32 s13, s45, 0
	s_lshl_b32 s0, s16, 10
	s_add_u32 s0, s0, s17
	s_lshl_b32 s0, s0, 1
	s_add_u32 s14, s6, s0
	s_addc_u32 s15, s7, 0
	s_add_u32 s14, s14, 0x8200000
	s_addc_u32 s15, s15, 0
	v_and_b32_e32 v26, 0x7f, v194
	v_lshrrev_b32_e32 v27, 7, v194
	v_lshlrev_b32_e32 v0, 2, v26
	v_lshl_add_u32 v1, v27, 9, v0
	v_add_u32_e32 v1, 0xd800, v1
	v_mul_u32_u24_e32 v2, 0x880, v27
	v_lshl_add_u32 v2, v26, 1, v2
	v_mul_u32_u24_e32 v4, 0x50, v26
	v_lshl_add_u32 v4, v27, 4, v4
	v_mul_u32_u24_e32 v200, 0x6000, v27
	v_add_u32_e32 v14, v200, v0
	v_add_u32_e32 v15, 0x1800, v14
	v_add_u32_e32 v16, 0x3000, v14
	v_add_u32_e32 v17, 0x4800, v14
	v_mul_u32_u24_e32 v200, 0x3000, v27
	v_lshl_add_u32 v18, v26, 1, v200
	v_add_u32_e32 v19, 0x1200, v18
	v_add_u32_e32 v20, 0x2400, v18
	v_cmp_lt_u32_e32 vcc, 0, v27
	s_nop 1
	v_cndmask_b32_e64 v21, 0, 1.0, vcc
	v_cmp_lt_u32_e32 vcc, 1, v27
	s_nop 1
	v_cndmask_b32_e64 v22, 0, 1.0, vcc
	v_cmp_lt_u32_e32 vcc, 2, v27
	s_nop 1
	v_cndmask_b32_e64 v23, 0, 1.0, vcc
	v_mov_b32_e32 v24, 0
	v_and_b32_e32 v26, 15, v197
	v_lshrrev_b32_e32 v27, 4, v197
	v_readfirstlane_b32 s18, v194
	s_nop 3
	s_lshr_b32 s18, s18, 6
	v_mul_u32_u24_e32 v5, 0x110, v26
	v_lshl_add_u32 v6, v27, 3, v5
	v_lshl_add_u32 v5, v27, 4, v5
	v_mul_u32_u24_e32 v9, 0x50, v26
	v_lshl_add_u32 v9, v27, 4, v9
	s_mul_i32 s19, s18, 0x500
	v_add_u32_e32 v8, s19, v9
	v_mul_u32_u24_e32 v7, 0x50, v26
	v_lshl_add_u32 v7, v27, 3, v7
	v_add_u32_e32 v7, s19, v7
	v_lshlrev_b32_e32 v10, 4, v27
	v_mul_u32_u24_e32 v11, 0x840, v27
	v_lshl_add_u32 v11, v26, 2, v11
	s_lshl_b32 s19, s18, 6
	v_add_u32_e32 v11, s19, v11
	v_add_u32_e32 v11, 0x9600, v11
	v_lshrrev_b32_e32 v200, 4, v194
	v_and_b32_e32 v201, 15, v194
	v_mul_u32_u24_e32 v12, 0x210, v200
	v_lshl_add_u32 v12, v201, 5, v12
	v_add_u32_e32 v12, 0x9600, v12
	v_lshlrev_b32_e32 v13, 11, v200
	v_lshl_add_u32 v13, v201, 4, v13
	v_lshlrev_b32_e32 v25, 11, v27
	v_lshl_add_u32 v25, v26, 2, v25
	v_add_u32_e32 v25, s19, v25
	v_lshlrev_b32_e32 v200, 2, v27
	v_add_u32_e32 v201, 0, v200
	v_cmp_le_u32_e64 s[40:41], v201, v26
	v_add_u32_e32 v201, 1, v200
	v_cmp_le_u32_e64 s[42:43], v201, v26
	v_add_u32_e32 v201, 2, v200
	v_cmp_le_u32_e64 s[44:45], v201, v26
	v_add_u32_e32 v201, 3, v200
	v_cmp_le_u32_e64 s[46:47], v201, v26
	v_mov_b32_e32 v92, 0
	v_mov_b32_e32 v93, 0
	v_mov_b32_e32 v94, 0
	v_mov_b32_e32 v95, 0
	v_mov_b32_e32 v96, 0
	v_mov_b32_e32 v97, 0
	v_mov_b32_e32 v98, 0
	v_mov_b32_e32 v99, 0
	v_mov_b32_e32 v100, 0
	v_mov_b32_e32 v101, 0
	v_mov_b32_e32 v102, 0
	v_mov_b32_e32 v103, 0
	v_mov_b32_e32 v104, 0
	v_mov_b32_e32 v105, 0
	v_mov_b32_e32 v106, 0
	v_mov_b32_e32 v107, 0
	v_mov_b32_e32 v108, 0
	v_mov_b32_e32 v109, 0
	v_mov_b32_e32 v110, 0
	v_mov_b32_e32 v111, 0
	v_mov_b32_e32 v112, 0
	v_mov_b32_e32 v113, 0
	v_mov_b32_e32 v114, 0
	v_mov_b32_e32 v115, 0
	v_mov_b32_e32 v116, 0
	v_mov_b32_e32 v117, 0
	v_mov_b32_e32 v118, 0
	v_mov_b32_e32 v119, 0
	v_mov_b32_e32 v120, 0
	v_mov_b32_e32 v121, 0
	v_mov_b32_e32 v122, 0
	v_mov_b32_e32 v123, 0
	v_mov_b32_e32 v26, v0
	global_load_dword v28, v14, s[4:5]
	global_load_dword v29, v14, s[4:5] offset:3072
	global_load_dword v30, v15, s[4:5]
	global_load_dword v31, v15, s[4:5] offset:3072
	global_load_dword v32, v16, s[4:5]
	global_load_dword v33, v16, s[4:5] offset:3072
	global_load_dword v34, v17, s[4:5]
	global_load_dword v35, v17, s[4:5] offset:3072
	s_add_u32 s4, s4, 0x18000
	s_addc_u32 s5, s5, 0
	global_load_ushort v36, v18, s[8:9]
	global_load_ushort v37, v18, s[8:9] offset:1536
	global_load_ushort v38, v18, s[8:9] offset:3072
	global_load_ushort v39, v19, s[8:9]
	global_load_ushort v40, v19, s[8:9] offset:1536
	global_load_ushort v41, v19, s[8:9] offset:3072
	global_load_ushort v42, v20, s[8:9]
	global_load_ushort v43, v20, s[8:9] offset:1536
	global_load_ushort v44, v18, s[10:11]
	global_load_ushort v45, v18, s[10:11] offset:1536
	global_load_ushort v46, v18, s[10:11] offset:3072
	global_load_ushort v47, v19, s[10:11]
	global_load_ushort v48, v19, s[10:11] offset:1536
	global_load_ushort v49, v19, s[10:11] offset:3072
	global_load_ushort v50, v20, s[10:11]
	global_load_ushort v51, v20, s[10:11] offset:1536
	s_add_u32 s8, s8, 0xc000
	s_addc_u32 s9, s9, 0
	s_add_u32 s10, s10, 0xc000
	s_addc_u32 s11, s11, 0
	global_load_dword v52, v14, s[4:5]
	global_load_dword v53, v14, s[4:5] offset:3072
	global_load_dword v54, v15, s[4:5]
	global_load_dword v55, v15, s[4:5] offset:3072
	global_load_dword v56, v16, s[4:5]
	global_load_dword v57, v16, s[4:5] offset:3072
	global_load_dword v58, v17, s[4:5]
	global_load_dword v59, v17, s[4:5] offset:3072
	s_add_u32 s4, s4, 0x18000
	s_addc_u32 s5, s5, 0
	global_load_ushort v60, v18, s[8:9]
	global_load_ushort v61, v18, s[8:9] offset:1536
	global_load_ushort v62, v18, s[8:9] offset:3072
	global_load_ushort v63, v19, s[8:9]
	global_load_ushort v64, v19, s[8:9] offset:1536
	global_load_ushort v65, v19, s[8:9] offset:3072
	global_load_ushort v66, v20, s[8:9]
	global_load_ushort v67, v20, s[8:9] offset:1536
	global_load_ushort v68, v18, s[10:11]
	global_load_ushort v69, v18, s[10:11] offset:1536
	global_load_ushort v70, v18, s[10:11] offset:3072
	global_load_ushort v71, v19, s[10:11]
	global_load_ushort v72, v19, s[10:11] offset:1536
	global_load_ushort v73, v19, s[10:11] offset:3072
	global_load_ushort v74, v20, s[10:11]
	global_load_ushort v75, v20, s[10:11] offset:1536
	s_add_u32 s8, s8, 0xc000
	s_addc_u32 s9, s9, 0
	s_add_u32 s10, s10, 0xc000
	s_addc_u32 s11, s11, 0
	global_load_dword v76, v14, s[4:5]
	global_load_dword v77, v14, s[4:5] offset:3072
	global_load_dword v78, v15, s[4:5]
	global_load_dword v79, v15, s[4:5] offset:3072
	global_load_dword v80, v16, s[4:5]
	global_load_dword v81, v16, s[4:5] offset:3072
	global_load_dword v82, v17, s[4:5]
	global_load_dword v83, v17, s[4:5] offset:3072
	s_add_u32 s4, s4, 0x18000
	s_addc_u32 s5, s5, 0
	s_waitcnt vmcnt(48)
	v_add_f32_e32 v200, v28, v29
	v_add_f32_e32 v200, v200, v30
	v_add_f32_e32 v200, v200, v31
	v_add_f32_e32 v200, v200, v32
	v_add_f32_e32 v200, v200, v33
	v_add_f32_e32 v200, v200, v34
	v_add_f32_e32 v200, v200, v35
	ds_write_b32 v1, v200
	s_waitcnt lgkmcnt(0)
	s_barrier
	s_waitcnt vmcnt(32)
	ds_read_b32 v200, v0 offset:55296
	ds_read_b32 v201, v0 offset:55808
	ds_read_b32 v202, v0 offset:56320
	ds_read_b32 v203, v0 offset:56832
	v_lshl_or_b32 v220, v45, 16, v44
	v_lshl_or_b32 v221, v47, 16, v46
	v_lshl_or_b32 v222, v49, 16, v48
	v_lshl_or_b32 v223, v51, 16, v50
	ds_write_b128 v4, v[220:223] offset:27648
	s_waitcnt lgkmcnt(1)
	v_mul_f32_e32 v204, v21, v200
	v_fmac_f32_e32 v204, v22, v201
	v_fmac_f32_e32 v204, v23, v202
	v_add_f32_e32 v205, v200, v201
	v_add_f32_e32 v205, v205, v202
	v_add_f32_e32 v205, v205, v203
	v_mov_b32_e32 v219, v28
	v_add_f32_e32 v218, v204, v219
	v_mul_f32_e32 v207, 0x3fb8aa3b, v28
	v_exp_f32_e32 v207, v207
	v_lshlrev_b32_e32 v209, 16, v36
	v_sub_f32_e32 v208, 1.0, v207
	v_mul_f32_e32 v207, 0x3fb8aa3b, v218
	v_exp_f32_e32 v207, v207
	v_add_f32_e32 v206, v218, v24
	v_mul_f32_e32 v224, v209, v207
	v_mul_f32_e32 v206, 0x3fb8aa3b, v206
	v_exp_f32_e32 v206, v206
	v_sub_f32_e32 v207, v205, v218
	v_mul_f32_e32 v28, v209, v206
	v_mul_f32_e32 v207, 0x3fb8aa3b, v207
	v_exp_f32_e32 v207, v207
	v_min_f32_e64 v206, -v218, s29
	v_mul_f32_e32 v210, v208, v207
	v_mul_f32_e32 v206, 0x3fb8aa3b, v206
	v_exp_f32_e32 v206, v206
	s_nop 0
	v_mul_f32_e32 v232, v208, v206
	v_add_f32_e32 v219, v219, v29
	v_add_f32_e32 v218, v204, v219
	v_mul_f32_e32 v207, 0x3fb8aa3b, v29
	v_exp_f32_e32 v207, v207
	v_lshlrev_b32_e32 v209, 16, v37
	v_sub_f32_e32 v208, 1.0, v207
	v_mul_f32_e32 v207, 0x3fb8aa3b, v218
	v_exp_f32_e32 v207, v207
	v_add_f32_e32 v206, v218, v24
	v_mul_f32_e32 v225, v209, v207
	v_mul_f32_e32 v206, 0x3fb8aa3b, v206
	v_exp_f32_e32 v206, v206
	v_sub_f32_e32 v207, v205, v218
	v_mul_f32_e32 v29, v209, v206
	v_mul_f32_e32 v207, 0x3fb8aa3b, v207
	v_exp_f32_e32 v207, v207
	v_min_f32_e64 v206, -v218, s29
	v_mul_f32_e32 v211, v208, v207
	v_mul_f32_e32 v206, 0x3fb8aa3b, v206
	v_exp_f32_e32 v206, v206
	s_nop 0
	v_mul_f32_e32 v233, v208, v206
	v_add_f32_e32 v219, v219, v30
	v_add_f32_e32 v218, v204, v219
	v_mul_f32_e32 v207, 0x3fb8aa3b, v30
	v_exp_f32_e32 v207, v207
	v_lshlrev_b32_e32 v209, 16, v38
	v_sub_f32_e32 v208, 1.0, v207
	v_mul_f32_e32 v207, 0x3fb8aa3b, v218
	v_exp_f32_e32 v207, v207
	v_add_f32_e32 v206, v218, v24
	v_mul_f32_e32 v226, v209, v207
	v_mul_f32_e32 v206, 0x3fb8aa3b, v206
	v_exp_f32_e32 v206, v206
	v_sub_f32_e32 v207, v205, v218
	v_mul_f32_e32 v30, v209, v206
	v_mul_f32_e32 v207, 0x3fb8aa3b, v207
	v_exp_f32_e32 v207, v207
	v_min_f32_e64 v206, -v218, s29
	v_mul_f32_e32 v212, v208, v207
	v_mul_f32_e32 v206, 0x3fb8aa3b, v206
	v_exp_f32_e32 v206, v206
	s_nop 0
	v_mul_f32_e32 v234, v208, v206
	v_add_f32_e32 v219, v219, v31
	v_add_f32_e32 v218, v204, v219
	v_mul_f32_e32 v207, 0x3fb8aa3b, v31
	v_exp_f32_e32 v207, v207
	v_lshlrev_b32_e32 v209, 16, v39
	v_sub_f32_e32 v208, 1.0, v207
	v_mul_f32_e32 v207, 0x3fb8aa3b, v218
	v_exp_f32_e32 v207, v207
	v_add_f32_e32 v206, v218, v24
	v_mul_f32_e32 v227, v209, v207
	v_mul_f32_e32 v206, 0x3fb8aa3b, v206
	v_exp_f32_e32 v206, v206
	v_sub_f32_e32 v207, v205, v218
	v_mul_f32_e32 v31, v209, v206
	v_mul_f32_e32 v207, 0x3fb8aa3b, v207
	v_exp_f32_e32 v207, v207
	v_min_f32_e64 v206, -v218, s29
	v_mul_f32_e32 v213, v208, v207
	v_mul_f32_e32 v206, 0x3fb8aa3b, v206
	v_exp_f32_e32 v206, v206
	s_nop 0
	v_mul_f32_e32 v235, v208, v206
	v_add_f32_e32 v219, v219, v32
	v_add_f32_e32 v218, v204, v219
	v_mul_f32_e32 v207, 0x3fb8aa3b, v32
	v_exp_f32_e32 v207, v207
	v_lshlrev_b32_e32 v209, 16, v40
	v_sub_f32_e32 v208, 1.0, v207
	v_mul_f32_e32 v207, 0x3fb8aa3b, v218
	v_exp_f32_e32 v207, v207
	v_add_f32_e32 v206, v218, v24
	v_mul_f32_e32 v228, v209, v207
	v_mul_f32_e32 v206, 0x3fb8aa3b, v206
	v_exp_f32_e32 v206, v206
	v_sub_f32_e32 v207, v205, v218
	v_mul_f32_e32 v32, v209, v206
	v_mul_f32_e32 v207, 0x3fb8aa3b, v207
	v_exp_f32_e32 v207, v207
	v_min_f32_e64 v206, -v218, s29
	v_mul_f32_e32 v214, v208, v207
	v_mul_f32_e32 v206, 0x3fb8aa3b, v206
	v_exp_f32_e32 v206, v206
	s_nop 0
	v_mul_f32_e32 v236, v208, v206
	v_add_f32_e32 v219, v219, v33
	v_add_f32_e32 v218, v204, v219
	v_mul_f32_e32 v207, 0x3fb8aa3b, v33
	v_exp_f32_e32 v207, v207
	v_lshlrev_b32_e32 v209, 16, v41
	v_sub_f32_e32 v208, 1.0, v207
	v_mul_f32_e32 v207, 0x3fb8aa3b, v218
	v_exp_f32_e32 v207, v207
	v_add_f32_e32 v206, v218, v24
	v_mul_f32_e32 v229, v209, v207
	v_mul_f32_e32 v206, 0x3fb8aa3b, v206
	v_exp_f32_e32 v206, v206
	v_sub_f32_e32 v207, v205, v218
	v_mul_f32_e32 v33, v209, v206
	v_mul_f32_e32 v207, 0x3fb8aa3b, v207
	v_exp_f32_e32 v207, v207
	v_min_f32_e64 v206, -v218, s29
	v_mul_f32_e32 v215, v208, v207
	v_mul_f32_e32 v206, 0x3fb8aa3b, v206
	v_exp_f32_e32 v206, v206
	s_nop 0
	v_mul_f32_e32 v237, v208, v206
	v_add_f32_e32 v219, v219, v34
	v_add_f32_e32 v218, v204, v219
	v_mul_f32_e32 v207, 0x3fb8aa3b, v34
	v_exp_f32_e32 v207, v207
	v_lshlrev_b32_e32 v209, 16, v42
	v_sub_f32_e32 v208, 1.0, v207
	v_mul_f32_e32 v207, 0x3fb8aa3b, v218
	v_exp_f32_e32 v207, v207
	v_add_f32_e32 v206, v218, v24
	v_mul_f32_e32 v230, v209, v207
	v_mul_f32_e32 v206, 0x3fb8aa3b, v206
	v_exp_f32_e32 v206, v206
	v_sub_f32_e32 v207, v205, v218
	v_mul_f32_e32 v34, v209, v206
	v_mul_f32_e32 v207, 0x3fb8aa3b, v207
	v_exp_f32_e32 v207, v207
	v_min_f32_e64 v206, -v218, s29
	v_mul_f32_e32 v216, v208, v207
	v_mul_f32_e32 v206, 0x3fb8aa3b, v206
	v_exp_f32_e32 v206, v206
	s_nop 0
	v_mul_f32_e32 v238, v208, v206
	v_add_f32_e32 v219, v219, v35
	v_add_f32_e32 v218, v204, v219
	v_mul_f32_e32 v207, 0x3fb8aa3b, v35
	v_exp_f32_e32 v207, v207
	v_lshlrev_b32_e32 v209, 16, v43
	v_sub_f32_e32 v208, 1.0, v207
	v_mul_f32_e32 v207, 0x3fb8aa3b, v218
	v_exp_f32_e32 v207, v207
	v_add_f32_e32 v206, v218, v24
	v_mul_f32_e32 v231, v209, v207
	v_mul_f32_e32 v206, 0x3fb8aa3b, v206
	v_exp_f32_e32 v206, v206
	v_sub_f32_e32 v207, v205, v218
	v_mul_f32_e32 v35, v209, v206
	v_mul_f32_e32 v207, 0x3fb8aa3b, v207
	v_exp_f32_e32 v207, v207
	v_min_f32_e64 v206, -v218, s29
	v_mul_f32_e32 v217, v208, v207
	v_mul_f32_e32 v206, 0x3fb8aa3b, v206
	v_exp_f32_e32 v206, v206
	s_nop 0
	v_mul_f32_e32 v239, v208, v206
	v_cvt_pk_bf16_f32 v224, v224, v225
	ds_write_b16 v2, v224
	ds_write_b16_d16_hi v2, v224 offset:272
	v_cvt_pk_bf16_f32 v232, v232, v233
	ds_write_b16 v2, v232 offset:8704
	ds_write_b16_d16_hi v2, v232 offset:8976
	v_cvt_pk_bf16_f32 v226, v226, v227
	ds_write_b16 v2, v226 offset:544
	ds_write_b16_d16_hi v2, v226 offset:816
	v_cvt_pk_bf16_f32 v234, v234, v235
	ds_write_b16 v2, v234 offset:9248
	ds_write_b16_d16_hi v2, v234 offset:9520
	v_cvt_pk_bf16_f32 v228, v228, v229
	ds_write_b16 v2, v228 offset:1088
	ds_write_b16_d16_hi v2, v228 offset:1360
	v_cvt_pk_bf16_f32 v236, v236, v237
	ds_write_b16 v2, v236 offset:9792
	ds_write_b16_d16_hi v2, v236 offset:10064
	v_cvt_pk_bf16_f32 v230, v230, v231
	ds_write_b16 v2, v230 offset:1632
	ds_write_b16_d16_hi v2, v230 offset:1904
	v_cvt_pk_bf16_f32 v238, v238, v239
	ds_write_b16 v2, v238 offset:10336
	ds_write_b16_d16_hi v2, v238 offset:10608
	v_cvt_pk_bf16_f32 v210, v210, v211
	v_cvt_pk_bf16_f32 v211, v212, v213
	v_cvt_pk_bf16_f32 v212, v214, v215
	v_cvt_pk_bf16_f32 v213, v216, v217
	ds_write_b128 v4, v[210:213] offset:17408
	v_cvt_pk_bf16_f32 v28, v28, v29
	v_cvt_pk_bf16_f32 v30, v30, v31
	v_cvt_pk_bf16_f32 v32, v32, v33
	v_cvt_pk_bf16_f32 v34, v34, v35
	global_store_short v18, v28, s[12:13]
	global_store_short_d16_hi v18, v28, s[12:13] offset:1536
	global_store_short v18, v30, s[12:13] offset:3072
	global_store_short_d16_hi v19, v30, s[12:13]
	global_store_short v19, v32, s[12:13] offset:1536
	global_store_short_d16_hi v19, v32, s[12:13] offset:3072
	global_store_short v20, v34, s[12:13]
	global_store_short_d16_hi v20, v34, s[12:13] offset:1536
	s_add_u32 s12, s12, 0xc000
	s_addc_u32 s13, s13, 0
	s_cmp_gt_u32 s18, 1
	s_cbranch_scc1 .Lhg_w01_1
	v_mul_f32_e32 v207, 0x3fb8aa3b, v205
	v_exp_f32_e32 v207, v207
	s_nop 0
	ds_write_b32 v26, v207 offset:37888
.Lhg_w01_1:
	v_add_f32_e32 v24, v24, v205
	s_waitcnt vmcnt(8)
	v_add_f32_e32 v200, v52, v53
	v_add_f32_e32 v200, v200, v54
	v_add_f32_e32 v200, v200, v55
	v_add_f32_e32 v200, v200, v56
	v_add_f32_e32 v200, v200, v57
	v_add_f32_e32 v200, v200, v58
	v_add_f32_e32 v200, v200, v59
	ds_write_b32 v1, v200 offset:2048
	s_waitcnt lgkmcnt(0)
	s_barrier
	v_xor_b32_e32 v2, 0x10000, v2
	v_xor_b32_e32 v4, 0x10000, v4
	v_xor_b32_e32 v26, 0x10000, v26
	s_mov_b32 s28, 0
.Lhg_loop:
	s_cmp_gt_u32 s28, 28
	s_cbranch_scc1 .Lhg_nolf_2
	global_load_dword v84, v14, s[4:5]
	global_load_dword v85, v14, s[4:5] offset:3072
	global_load_dword v86, v15, s[4:5]
	global_load_dword v87, v15, s[4:5] offset:3072
	global_load_dword v88, v16, s[4:5]
	global_load_dword v89, v16, s[4:5] offset:3072
	global_load_dword v90, v17, s[4:5]
	global_load_dword v91, v17, s[4:5] offset:3072
	s_add_u32 s4, s4, 0x18000
	s_addc_u32 s5, s5, 0
.Lhg_nolf_2:
	s_cmp_gt_u32 s28, 29
	s_cbranch_scc1 .Lhg_noqv_3
	global_load_ushort v36, v18, s[8:9]
	global_load_ushort v37, v18, s[8:9] offset:1536
	global_load_ushort v38, v18, s[8:9] offset:3072
	global_load_ushort v39, v19, s[8:9]
	global_load_ushort v40, v19, s[8:9] offset:1536
	global_load_ushort v41, v19, s[8:9] offset:3072
	global_load_ushort v42, v20, s[8:9]
	global_load_ushort v43, v20, s[8:9] offset:1536
	global_load_ushort v44, v18, s[10:11]
	global_load_ushort v45, v18, s[10:11] offset:1536
	global_load_ushort v46, v18, s[10:11] offset:3072
	global_load_ushort v47, v19, s[10:11]
	global_load_ushort v48, v19, s[10:11] offset:1536
	global_load_ushort v49, v19, s[10:11] offset:3072
	global_load_ushort v50, v20, s[10:11]
	global_load_ushort v51, v20, s[10:11] offset:1536
	s_add_u32 s8, s8, 0xc000
	s_addc_u32 s9, s9, 0
	s_add_u32 s10, s10, 0xc000
	s_addc_u32 s11, s11, 0
.Lhg_noqv_3:
	s_cmp_gt_u32 s18, 3
	s_cbranch_scc1 .Lhg_bfirst_4
	ds_read_b128 v[144:147], v5 offset:8704
	ds_read_b128 v[148:151], v5 offset:13056
	ds_read_b128 v[152:155], v5 offset:0
	ds_read_b128 v[172:175], v5 offset:4352
	ds_read_b128 v[176:179], v5 offset:8768
	ds_read_b128 v[180:183], v5 offset:13120
	ds_read_b128 v[184:187], v5 offset:64
	ds_read_b128 v[188:191], v5 offset:4416
	ds_read_b128 v[200:203], v5 offset:8832
	ds_read_b128 v[204:207], v5 offset:13184
	ds_read_b128 v[208:211], v5 offset:128
	ds_read_b128 v[212:215], v5 offset:4480
	s_waitcnt lgkmcnt(8)
	v_mfma_f32_16x16x32_bf16 v[124:127], v[144:147], v[152:155], 0
	v_mfma_f32_16x16x32_bf16 v[128:131], v[144:147], v[172:175], 0
	v_mfma_f32_16x16x32_bf16 v[132:135], v[148:151], v[172:175], 0
	ds_read_b128 v[216:219], v5 offset:8896
	ds_read_b128 v[220:223], v5 offset:13248
	ds_read_b128 v[224:227], v5 offset:192
	ds_read_b128 v[228:231], v5 offset:4544
	s_waitcnt lgkmcnt(8)
	v_mfma_f32_16x16x32_bf16 v[124:127], v[176:179], v[184:187], v[124:127]
	v_mfma_f32_16x16x32_bf16 v[128:131], v[176:179], v[188:191], v[128:131]
	v_mfma_f32_16x16x32_bf16 v[132:135], v[180:183], v[188:191], v[132:135]
	ds_read_b64 v[144:145], v6 offset:0
	ds_read_b64 v[146:147], v6 offset:32
	ds_read_b64 v[148:149], v6 offset:4352
	ds_read_b64 v[150:151], v6 offset:4384
	s_waitcnt lgkmcnt(8)
	v_mfma_f32_16x16x32_bf16 v[124:127], v[200:203], v[208:211], v[124:127]
	v_mfma_f32_16x16x32_bf16 v[128:131], v[200:203], v[212:215], v[128:131]
	v_mfma_f32_16x16x32_bf16 v[132:135], v[204:207], v[212:215], v[132:135]
	ds_read_b64 v[152:153], v6 offset:64
	ds_read_b64 v[154:155], v6 offset:96
	ds_read_b64 v[172:173], v6 offset:4416
	ds_read_b64 v[174:175], v6 offset:4448
	s_waitcnt lgkmcnt(8)
	v_mfma_f32_16x16x32_bf16 v[124:127], v[216:219], v[224:227], v[124:127]
	v_mfma_f32_16x16x32_bf16 v[128:131], v[216:219], v[228:231], v[128:131]
	v_mfma_f32_16x16x32_bf16 v[132:135], v[220:223], v[228:231], v[132:135]
	ds_read_b64 v[176:177], v6 offset:128
	ds_read_b64 v[178:179], v6 offset:160
	ds_read_b64 v[180:181], v6 offset:4480
	ds_read_b64 v[182:183], v6 offset:4512
	v_cvt_pk_bf16_f32 v232, v92, v93
	v_cvt_pk_bf16_f32 v233, v94, v95
	v_cvt_pk_bf16_f32 v234, v96, v97
	v_cvt_pk_bf16_f32 v235, v98, v99
	s_waitcnt lgkmcnt(8)
	s_nop 1
	v_mfma_f32_16x16x32_bf16 v[136:139], v[144:147], v[232:235], 0
	v_mfma_f32_16x16x32_bf16 v[140:143], v[148:151], v[232:235], 0
	ds_read_b64 v[184:185], v6 offset:192
	ds_read_b64 v[186:187], v6 offset:224
	ds_read_b64 v[188:189], v6 offset:4544
	ds_read_b64 v[190:191], v6 offset:4576
	v_cvt_pk_bf16_f32 v232, v100, v101
	v_cvt_pk_bf16_f32 v233, v102, v103
	v_cvt_pk_bf16_f32 v234, v104, v105
	v_cvt_pk_bf16_f32 v235, v106, v107
	s_waitcnt lgkmcnt(8)
	s_nop 1
	v_mfma_f32_16x16x32_bf16 v[136:139], v[152:155], v[232:235], v[136:139]
	v_mfma_f32_16x16x32_bf16 v[140:143], v[172:175], v[232:235], v[140:143]
	ds_read_b64 v[236:237], v7 offset:27648
	ds_read_b64 v[238:239], v7 offset:27680
	ds_read_b128 v[200:203], v8 offset:27648
	v_cvt_pk_bf16_f32 v232, v108, v109
	v_cvt_pk_bf16_f32 v233, v110, v111
	v_cvt_pk_bf16_f32 v234, v112, v113
	v_cvt_pk_bf16_f32 v235, v114, v115
	s_waitcnt lgkmcnt(7)
	s_nop 1
	v_mfma_f32_16x16x32_bf16 v[136:139], v[176:179], v[232:235], v[136:139]
	v_mfma_f32_16x16x32_bf16 v[140:143], v[180:183], v[232:235], v[140:143]
	ds_read_b128 v[204:207], v9 offset:17408
	ds_read_b128 v[208:211], v10 offset:37888
	v_cvt_pk_bf16_f32 v232, v116, v117
	v_cvt_pk_bf16_f32 v233, v118, v119
	v_cvt_pk_bf16_f32 v234, v120, v121
	v_cvt_pk_bf16_f32 v235, v122, v123
	s_waitcnt lgkmcnt(5)
	s_nop 1
	v_mfma_f32_16x16x32_bf16 v[136:139], v[184:187], v[232:235], v[136:139]
	v_mfma_f32_16x16x32_bf16 v[140:143], v[188:191], v[232:235], v[140:143]
	ds_read_b128 v[212:215], v9 offset:18688
	ds_read_b128 v[216:219], v10 offset:37952
	v_cndmask_b32_e64 v124, 0, v124, s[40:41]
	v_cndmask_b32_e64 v132, 0, v132, s[40:41]
	v_cndmask_b32_e64 v125, 0, v125, s[42:43]
	v_cndmask_b32_e64 v133, 0, v133, s[42:43]
	v_cndmask_b32_e64 v126, 0, v126, s[44:45]
	v_cndmask_b32_e64 v134, 0, v134, s[44:45]
	v_cndmask_b32_e64 v127, 0, v127, s[46:47]
	v_cndmask_b32_e64 v135, 0, v135, s[46:47]
	v_cvt_pk_bf16_f32 v124, v124, v125
	v_cvt_pk_bf16_f32 v125, v126, v127
	v_mov_b32_e32 v126, 0
	v_mov_b32_e32 v127, 0
	v_cvt_pk_bf16_f32 v128, v128, v129
	v_cvt_pk_bf16_f32 v129, v130, v131
	v_cvt_pk_bf16_f32 v130, v132, v133
	v_cvt_pk_bf16_f32 v131, v134, v135
	s_waitcnt lgkmcnt(4)
	s_nop 1
	v_mfma_f32_16x16x32_bf16 v[136:139], v[124:127], v[236:239], v[136:139]
	v_mfma_f32_16x16x32_bf16 v[140:143], v[128:131], v[236:239], v[140:143]
	ds_read_b128 v[220:223], v9 offset:19968
	ds_read_b128 v[224:227], v10 offset:38016
	ds_read_b128 v[228:231], v9 offset:21248
	ds_read_b128 v[144:147], v10 offset:38080
	s_waitcnt lgkmcnt(6)
	v_pk_mul_f32 v[92:93], v[92:93], v[208:209]
	v_pk_mul_f32 v[94:95], v[94:95], v[210:211]
	s_nop 1
	v_mfma_f32_16x16x32_bf16 v[92:95], v[204:207], v[200:203], v[92:95]
	ds_read_b128 v[152:155], v9 offset:22528
	ds_read_b128 v[172:175], v10 offset:38144
	s_waitcnt lgkmcnt(6)
	v_pk_mul_f32 v[96:97], v[96:97], v[216:217]
	v_pk_mul_f32 v[98:99], v[98:99], v[218:219]
	s_nop 1
	v_mfma_f32_16x16x32_bf16 v[96:99], v[212:215], v[200:203], v[96:99]
	ds_read_b128 v[176:179], v9 offset:23808
	ds_read_b128 v[180:183], v10 offset:38208
	s_waitcnt lgkmcnt(6)
	v_pk_mul_f32 v[100:101], v[100:101], v[224:225]
	v_pk_mul_f32 v[102:103], v[102:103], v[226:227]
	s_nop 1
	v_mfma_f32_16x16x32_bf16 v[100:103], v[220:223], v[200:203], v[100:103]
	ds_read_b128 v[184:187], v9 offset:25088
	ds_read_b128 v[188:191], v10 offset:38272
	s_waitcnt lgkmcnt(6)
	v_pk_mul_f32 v[104:105], v[104:105], v[144:145]
	v_pk_mul_f32 v[106:107], v[106:107], v[146:147]
	s_nop 1
	v_mfma_f32_16x16x32_bf16 v[104:107], v[228:231], v[200:203], v[104:107]
	ds_read_b128 v[204:207], v9 offset:26368
	ds_read_b128 v[208:211], v10 offset:38336
	s_waitcnt lgkmcnt(6)
	v_pk_mul_f32 v[108:109], v[108:109], v[172:173]
	v_pk_mul_f32 v[110:111], v[110:111], v[174:175]
	s_nop 1
	v_mfma_f32_16x16x32_bf16 v[108:111], v[152:155], v[200:203], v[108:111]
	s_waitcnt lgkmcnt(4)
	v_pk_mul_f32 v[112:113], v[112:113], v[180:181]
	v_pk_mul_f32 v[114:115], v[114:115], v[182:183]
	s_nop 1
	v_mfma_f32_16x16x32_bf16 v[112:115], v[176:179], v[200:203], v[112:115]
	s_waitcnt lgkmcnt(2)
	v_pk_mul_f32 v[116:117], v[116:117], v[188:189]
	v_pk_mul_f32 v[118:119], v[118:119], v[190:191]
	s_nop 1
	v_mfma_f32_16x16x32_bf16 v[116:119], v[184:187], v[200:203], v[116:119]
	s_waitcnt lgkmcnt(0)
	v_pk_mul_f32 v[120:121], v[120:121], v[208:209]
	v_pk_mul_f32 v[122:123], v[122:123], v[210:211]
	s_nop 1
	v_mfma_f32_16x16x32_bf16 v[120:123], v[204:207], v[200:203], v[120:123]
	ds_write_b32 v11, v136
	ds_write_b32 v11, v140 offset:8448
	ds_write_b32 v11, v137 offset:528
	ds_write_b32 v11, v141 offset:8976
	ds_write_b32 v11, v138 offset:1056
	ds_write_b32 v11, v142 offset:9504
	ds_write_b32 v11, v139 offset:1584
	ds_write_b32 v11, v143 offset:10032
	s_cmp_gt_u32 s28, 28
	s_cbranch_scc1 .Lhg_wq29_6
	s_waitcnt vmcnt(33)
	s_branch .Lhg_wqj_8
.Lhg_wq29_6:
	s_cmp_gt_u32 s28, 29
	s_cbranch_scc1 .Lhg_wq30_7
	s_waitcnt vmcnt(16)
	s_branch .Lhg_wqj_8

.Lhg_wqj_8:
	ds_read_b32 v200, v0 offset:57344
	ds_read_b32 v201, v0 offset:57856
	ds_read_b32 v202, v0 offset:58368
	ds_read_b32 v203, v0 offset:58880
	v_lshl_or_b32 v220, v69, 16, v68
	v_lshl_or_b32 v221, v71, 16, v70
	v_lshl_or_b32 v222, v73, 16, v72
	v_lshl_or_b32 v223, v75, 16, v74
	ds_write_b128 v4, v[220:223] offset:27648
	s_waitcnt lgkmcnt(1)
	v_mul_f32_e32 v204, v21, v200
	v_fmac_f32_e32 v204, v22, v201
	v_fmac_f32_e32 v204, v23, v202
	v_add_f32_e32 v205, v200, v201
	v_add_f32_e32 v205, v205, v202
	v_add_f32_e32 v205, v205, v203
	v_mov_b32_e32 v219, v52
	v_add_f32_e32 v218, v204, v219
	v_mul_f32_e32 v207, 0x3fb8aa3b, v52
	v_exp_f32_e32 v207, v207
	v_lshlrev_b32_e32 v209, 16, v60
	v_sub_f32_e32 v208, 1.0, v207
	v_mul_f32_e32 v207, 0x3fb8aa3b, v218
	v_exp_f32_e32 v207, v207
	v_add_f32_e32 v206, v218, v24
	v_mul_f32_e32 v224, v209, v207
	v_mul_f32_e32 v206, 0x3fb8aa3b, v206
	v_exp_f32_e32 v206, v206
	v_sub_f32_e32 v207, v205, v218
	v_mul_f32_e32 v52, v209, v206
	v_mul_f32_e32 v207, 0x3fb8aa3b, v207
	v_exp_f32_e32 v207, v207
	v_min_f32_e64 v206, -v218, s29
	v_mul_f32_e32 v210, v208, v207
	v_mul_f32_e32 v206, 0x3fb8aa3b, v206
	v_exp_f32_e32 v206, v206
	s_nop 0
	v_mul_f32_e32 v232, v208, v206
	v_add_f32_e32 v219, v219, v53
	v_add_f32_e32 v218, v204, v219
	v_mul_f32_e32 v207, 0x3fb8aa3b, v53
	v_exp_f32_e32 v207, v207
	v_lshlrev_b32_e32 v209, 16, v61
	v_sub_f32_e32 v208, 1.0, v207
	v_mul_f32_e32 v207, 0x3fb8aa3b, v218
	v_exp_f32_e32 v207, v207
	v_add_f32_e32 v206, v218, v24
	v_mul_f32_e32 v225, v209, v207
	v_mul_f32_e32 v206, 0x3fb8aa3b, v206
	v_exp_f32_e32 v206, v206
	v_sub_f32_e32 v207, v205, v218
	v_mul_f32_e32 v53, v209, v206
	v_mul_f32_e32 v207, 0x3fb8aa3b, v207
	v_exp_f32_e32 v207, v207
	v_min_f32_e64 v206, -v218, s29
	v_mul_f32_e32 v211, v208, v207
	v_mul_f32_e32 v206, 0x3fb8aa3b, v206
	v_exp_f32_e32 v206, v206
	s_nop 0
	v_mul_f32_e32 v233, v208, v206
	v_add_f32_e32 v219, v219, v54
	v_add_f32_e32 v218, v204, v219
	v_mul_f32_e32 v207, 0x3fb8aa3b, v54
	v_exp_f32_e32 v207, v207
	v_lshlrev_b32_e32 v209, 16, v62
	v_sub_f32_e32 v208, 1.0, v207
	v_mul_f32_e32 v207, 0x3fb8aa3b, v218
	v_exp_f32_e32 v207, v207
	v_add_f32_e32 v206, v218, v24
	v_mul_f32_e32 v226, v209, v207
	v_mul_f32_e32 v206, 0x3fb8aa3b, v206
	v_exp_f32_e32 v206, v206
	v_sub_f32_e32 v207, v205, v218
	v_mul_f32_e32 v54, v209, v206
	v_mul_f32_e32 v207, 0x3fb8aa3b, v207
	v_exp_f32_e32 v207, v207
	v_min_f32_e64 v206, -v218, s29
	v_mul_f32_e32 v212, v208, v207
	v_mul_f32_e32 v206, 0x3fb8aa3b, v206
	v_exp_f32_e32 v206, v206
	s_nop 0
	v_mul_f32_e32 v234, v208, v206
	v_add_f32_e32 v219, v219, v55
	v_add_f32_e32 v218, v204, v219
	v_mul_f32_e32 v207, 0x3fb8aa3b, v55
	v_exp_f32_e32 v207, v207
	v_lshlrev_b32_e32 v209, 16, v63
	v_sub_f32_e32 v208, 1.0, v207
	v_mul_f32_e32 v207, 0x3fb8aa3b, v218
	v_exp_f32_e32 v207, v207
	v_add_f32_e32 v206, v218, v24
	v_mul_f32_e32 v227, v209, v207
	v_mul_f32_e32 v206, 0x3fb8aa3b, v206
	v_exp_f32_e32 v206, v206
	v_sub_f32_e32 v207, v205, v218
	v_mul_f32_e32 v55, v209, v206
	v_mul_f32_e32 v207, 0x3fb8aa3b, v207
	v_exp_f32_e32 v207, v207
	v_min_f32_e64 v206, -v218, s29
	v_mul_f32_e32 v213, v208, v207
	v_mul_f32_e32 v206, 0x3fb8aa3b, v206
	v_exp_f32_e32 v206, v206
	s_nop 0
	v_mul_f32_e32 v235, v208, v206
	v_add_f32_e32 v219, v219, v56
	v_add_f32_e32 v218, v204, v219
	v_mul_f32_e32 v207, 0x3fb8aa3b, v56
	v_exp_f32_e32 v207, v207
	v_lshlrev_b32_e32 v209, 16, v64
	v_sub_f32_e32 v208, 1.0, v207
	v_mul_f32_e32 v207, 0x3fb8aa3b, v218
	v_exp_f32_e32 v207, v207
	v_add_f32_e32 v206, v218, v24
	v_mul_f32_e32 v228, v209, v207
	v_mul_f32_e32 v206, 0x3fb8aa3b, v206
	v_exp_f32_e32 v206, v206
	v_sub_f32_e32 v207, v205, v218
	v_mul_f32_e32 v56, v209, v206
	v_mul_f32_e32 v207, 0x3fb8aa3b, v207
	v_exp_f32_e32 v207, v207
	v_min_f32_e64 v206, -v218, s29
	v_mul_f32_e32 v214, v208, v207
	v_mul_f32_e32 v206, 0x3fb8aa3b, v206
	v_exp_f32_e32 v206, v206
	s_nop 0
	v_mul_f32_e32 v236, v208, v206
	v_add_f32_e32 v219, v219, v57
	v_add_f32_e32 v218, v204, v219
	v_mul_f32_e32 v207, 0x3fb8aa3b, v57
	v_exp_f32_e32 v207, v207
	v_lshlrev_b32_e32 v209, 16, v65
	v_sub_f32_e32 v208, 1.0, v207
	v_mul_f32_e32 v207, 0x3fb8aa3b, v218
	v_exp_f32_e32 v207, v207
	v_add_f32_e32 v206, v218, v24
	v_mul_f32_e32 v229, v209, v207
	v_mul_f32_e32 v206, 0x3fb8aa3b, v206
	v_exp_f32_e32 v206, v206
	v_sub_f32_e32 v207, v205, v218
	v_mul_f32_e32 v57, v209, v206
	v_mul_f32_e32 v207, 0x3fb8aa3b, v207
	v_exp_f32_e32 v207, v207
	v_min_f32_e64 v206, -v218, s29
	v_mul_f32_e32 v215, v208, v207
	v_mul_f32_e32 v206, 0x3fb8aa3b, v206
	v_exp_f32_e32 v206, v206
	s_nop 0
	v_mul_f32_e32 v237, v208, v206
	v_add_f32_e32 v219, v219, v58
	v_add_f32_e32 v218, v204, v219
	v_mul_f32_e32 v207, 0x3fb8aa3b, v58
	v_exp_f32_e32 v207, v207
	v_lshlrev_b32_e32 v209, 16, v66
	v_sub_f32_e32 v208, 1.0, v207
	v_mul_f32_e32 v207, 0x3fb8aa3b, v218
	v_exp_f32_e32 v207, v207
	v_add_f32_e32 v206, v218, v24
	v_mul_f32_e32 v230, v209, v207
	v_mul_f32_e32 v206, 0x3fb8aa3b, v206
	v_exp_f32_e32 v206, v206
	v_sub_f32_e32 v207, v205, v218
	v_mul_f32_e32 v58, v209, v206
	v_mul_f32_e32 v207, 0x3fb8aa3b, v207
	v_exp_f32_e32 v207, v207
	v_min_f32_e64 v206, -v218, s29
	v_mul_f32_e32 v216, v208, v207
	v_mul_f32_e32 v206, 0x3fb8aa3b, v206
	v_exp_f32_e32 v206, v206
	s_nop 0
	v_mul_f32_e32 v238, v208, v206
	v_add_f32_e32 v219, v219, v59
	v_add_f32_e32 v218, v204, v219
	v_mul_f32_e32 v207, 0x3fb8aa3b, v59
	v_exp_f32_e32 v207, v207
	v_lshlrev_b32_e32 v209, 16, v67
	v_sub_f32_e32 v208, 1.0, v207
	v_mul_f32_e32 v207, 0x3fb8aa3b, v218
	v_exp_f32_e32 v207, v207
	v_add_f32_e32 v206, v218, v24
	v_mul_f32_e32 v231, v209, v207
	v_mul_f32_e32 v206, 0x3fb8aa3b, v206
	v_exp_f32_e32 v206, v206
	v_sub_f32_e32 v207, v205, v218
	v_mul_f32_e32 v59, v209, v206
	v_mul_f32_e32 v207, 0x3fb8aa3b, v207
	v_exp_f32_e32 v207, v207
	v_min_f32_e64 v206, -v218, s29
	v_mul_f32_e32 v217, v208, v207
	v_mul_f32_e32 v206, 0x3fb8aa3b, v206
	v_exp_f32_e32 v206, v206
	s_nop 0
	v_mul_f32_e32 v239, v208, v206
	v_cvt_pk_bf16_f32 v224, v224, v225
	ds_write_b16 v2, v224
	ds_write_b16_d16_hi v2, v224 offset:272
	v_cvt_pk_bf16_f32 v232, v232, v233
	ds_write_b16 v2, v232 offset:8704
	ds_write_b16_d16_hi v2, v232 offset:8976
	v_cvt_pk_bf16_f32 v226, v226, v227
	ds_write_b16 v2, v226 offset:544
	ds_write_b16_d16_hi v2, v226 offset:816
	v_cvt_pk_bf16_f32 v234, v234, v235
	ds_write_b16 v2, v234 offset:9248
	ds_write_b16_d16_hi v2, v234 offset:9520
	v_cvt_pk_bf16_f32 v228, v228, v229
	ds_write_b16 v2, v228 offset:1088
	ds_write_b16_d16_hi v2, v228 offset:1360
	v_cvt_pk_bf16_f32 v236, v236, v237
	ds_write_b16 v2, v236 offset:9792
	ds_write_b16_d16_hi v2, v236 offset:10064
	v_cvt_pk_bf16_f32 v230, v230, v231
	ds_write_b16 v2, v230 offset:1632
	ds_write_b16_d16_hi v2, v230 offset:1904
	v_cvt_pk_bf16_f32 v238, v238, v239
	ds_write_b16 v2, v238 offset:10336
	ds_write_b16_d16_hi v2, v238 offset:10608
	v_cvt_pk_bf16_f32 v210, v210, v211
	v_cvt_pk_bf16_f32 v211, v212, v213
	v_cvt_pk_bf16_f32 v212, v214, v215
	v_cvt_pk_bf16_f32 v213, v216, v217
	ds_write_b128 v4, v[210:213] offset:17408
	v_cvt_pk_bf16_f32 v52, v52, v53
	v_cvt_pk_bf16_f32 v54, v54, v55
	v_cvt_pk_bf16_f32 v56, v56, v57
	v_cvt_pk_bf16_f32 v58, v58, v59
	global_store_short v18, v52, s[12:13]
	global_store_short_d16_hi v18, v52, s[12:13] offset:1536
	global_store_short v18, v54, s[12:13] offset:3072
	global_store_short_d16_hi v19, v54, s[12:13]
	global_store_short v19, v56, s[12:13] offset:1536
	global_store_short_d16_hi v19, v56, s[12:13] offset:3072
	global_store_short v20, v58, s[12:13]
	global_store_short_d16_hi v20, v58, s[12:13] offset:1536
	s_add_u32 s12, s12, 0xc000
	s_addc_u32 s13, s13, 0
	s_cmp_gt_u32 s18, 1
	s_cbranch_scc1 .Lhg_w01_9
	v_mul_f32_e32 v207, 0x3fb8aa3b, v205
	v_exp_f32_e32 v207, v207
	s_nop 0
	ds_write_b32 v26, v207 offset:37888

.Lhg_bfirst_4:
	s_cmp_gt_u32 s28, 28
	s_cbranch_scc1 .Lhg_wq29_10
	s_waitcnt vmcnt(33)
	s_branch .Lhg_wqj_12

.Lhg_w01_13:
	v_add_f32_e32 v24, v24, v205
	ds_read_b128 v[144:147], v5 offset:8704
	ds_read_b128 v[148:151], v5 offset:13056
	ds_read_b128 v[152:155], v5 offset:0
	ds_read_b128 v[172:175], v5 offset:4352
	ds_read_b128 v[176:179], v5 offset:8768
	ds_read_b128 v[180:183], v5 offset:13120
	ds_read_b128 v[184:187], v5 offset:64
	ds_read_b128 v[188:191], v5 offset:4416
	ds_read_b128 v[200:203], v5 offset:8832
	ds_read_b128 v[204:207], v5 offset:13184
	ds_read_b128 v[208:211], v5 offset:128
	ds_read_b128 v[212:215], v5 offset:4480
	s_waitcnt lgkmcnt(8)
	v_mfma_f32_16x16x32_bf16 v[124:127], v[144:147], v[152:155], 0
	v_mfma_f32_16x16x32_bf16 v[128:131], v[144:147], v[172:175], 0
	v_mfma_f32_16x16x32_bf16 v[132:135], v[148:151], v[172:175], 0
	ds_read_b128 v[216:219], v5 offset:8896
	ds_read_b128 v[220:223], v5 offset:13248
	ds_read_b128 v[224:227], v5 offset:192
	ds_read_b128 v[228:231], v5 offset:4544
	s_waitcnt lgkmcnt(8)
	v_mfma_f32_16x16x32_bf16 v[124:127], v[176:179], v[184:187], v[124:127]
	v_mfma_f32_16x16x32_bf16 v[128:131], v[176:179], v[188:191], v[128:131]
	v_mfma_f32_16x16x32_bf16 v[132:135], v[180:183], v[188:191], v[132:135]
	ds_read_b64 v[144:145], v6 offset:0
	ds_read_b64 v[146:147], v6 offset:32
	ds_read_b64 v[148:149], v6 offset:4352
	ds_read_b64 v[150:151], v6 offset:4384
	s_waitcnt lgkmcnt(8)
	v_mfma_f32_16x16x32_bf16 v[124:127], v[200:203], v[208:211], v[124:127]
	v_mfma_f32_16x16x32_bf16 v[128:131], v[200:203], v[212:215], v[128:131]
	v_mfma_f32_16x16x32_bf16 v[132:135], v[204:207], v[212:215], v[132:135]
	ds_read_b64 v[152:153], v6 offset:64
	ds_read_b64 v[154:155], v6 offset:96
	ds_read_b64 v[172:173], v6 offset:4416
	ds_read_b64 v[174:175], v6 offset:4448
	s_waitcnt lgkmcnt(8)
	v_mfma_f32_16x16x32_bf16 v[124:127], v[216:219], v[224:227], v[124:127]
	v_mfma_f32_16x16x32_bf16 v[128:131], v[216:219], v[228:231], v[128:131]
	v_mfma_f32_16x16x32_bf16 v[132:135], v[220:223], v[228:231], v[132:135]
	ds_read_b64 v[176:177], v6 offset:128
	ds_read_b64 v[178:179], v6 offset:160
	ds_read_b64 v[180:181], v6 offset:4480
	ds_read_b64 v[182:183], v6 offset:4512
	v_cvt_pk_bf16_f32 v232, v92, v93
	v_cvt_pk_bf16_f32 v233, v94, v95
	v_cvt_pk_bf16_f32 v234, v96, v97
	v_cvt_pk_bf16_f32 v235, v98, v99
	s_waitcnt lgkmcnt(8)
	s_nop 1
	v_mfma_f32_16x16x32_bf16 v[136:139], v[144:147], v[232:235], 0
	v_mfma_f32_16x16x32_bf16 v[140:143], v[148:151], v[232:235], 0
	ds_read_b64 v[184:185], v6 offset:192
	ds_read_b64 v[186:187], v6 offset:224
	ds_read_b64 v[188:189], v6 offset:4544
	ds_read_b64 v[190:191], v6 offset:4576
	v_cvt_pk_bf16_f32 v232, v100, v101
	v_cvt_pk_bf16_f32 v233, v102, v103
	v_cvt_pk_bf16_f32 v234, v104, v105
	v_cvt_pk_bf16_f32 v235, v106, v107
	s_waitcnt lgkmcnt(8)
	s_nop 1
	v_mfma_f32_16x16x32_bf16 v[136:139], v[152:155], v[232:235], v[136:139]
	v_mfma_f32_16x16x32_bf16 v[140:143], v[172:175], v[232:235], v[140:143]
	ds_read_b64 v[236:237], v7 offset:27648
	ds_read_b64 v[238:239], v7 offset:27680
	ds_read_b128 v[200:203], v8 offset:27648
	v_cvt_pk_bf16_f32 v232, v108, v109
	v_cvt_pk_bf16_f32 v233, v110, v111
	v_cvt_pk_bf16_f32 v234, v112, v113
	v_cvt_pk_bf16_f32 v235, v114, v115
	s_waitcnt lgkmcnt(7)
	s_nop 1
	v_mfma_f32_16x16x32_bf16 v[136:139], v[176:179], v[232:235], v[136:139]
	v_mfma_f32_16x16x32_bf16 v[140:143], v[180:183], v[232:235], v[140:143]
	ds_read_b128 v[204:207], v9 offset:17408
	ds_read_b128 v[208:211], v10 offset:37888
	v_cvt_pk_bf16_f32 v232, v116, v117
	v_cvt_pk_bf16_f32 v233, v118, v119
	v_cvt_pk_bf16_f32 v234, v120, v121
	v_cvt_pk_bf16_f32 v235, v122, v123
	s_waitcnt lgkmcnt(5)
	s_nop 1
	v_mfma_f32_16x16x32_bf16 v[136:139], v[184:187], v[232:235], v[136:139]
	v_mfma_f32_16x16x32_bf16 v[140:143], v[188:191], v[232:235], v[140:143]
	ds_read_b128 v[212:215], v9 offset:18688
	ds_read_b128 v[216:219], v10 offset:37952
	v_cndmask_b32_e64 v124, 0, v124, s[40:41]
	v_cndmask_b32_e64 v132, 0, v132, s[40:41]
	v_cndmask_b32_e64 v125, 0, v125, s[42:43]
	v_cndmask_b32_e64 v133, 0, v133, s[42:43]
	v_cndmask_b32_e64 v126, 0, v126, s[44:45]
	v_cndmask_b32_e64 v134, 0, v134, s[44:45]
	v_cndmask_b32_e64 v127, 0, v127, s[46:47]
	v_cndmask_b32_e64 v135, 0, v135, s[46:47]
	v_cvt_pk_bf16_f32 v124, v124, v125
	v_cvt_pk_bf16_f32 v125, v126, v127
	v_mov_b32_e32 v126, 0
	v_mov_b32_e32 v127, 0
	v_cvt_pk_bf16_f32 v128, v128, v129
	v_cvt_pk_bf16_f32 v129, v130, v131
	v_cvt_pk_bf16_f32 v130, v132, v133
	v_cvt_pk_bf16_f32 v131, v134, v135
	s_waitcnt lgkmcnt(4)
	s_nop 1
	v_mfma_f32_16x16x32_bf16 v[136:139], v[124:127], v[236:239], v[136:139]
	v_mfma_f32_16x16x32_bf16 v[140:143], v[128:131], v[236:239], v[140:143]
	ds_read_b128 v[220:223], v9 offset:19968
	ds_read_b128 v[224:227], v10 offset:38016
	ds_read_b128 v[228:231], v9 offset:21248
	ds_read_b128 v[144:147], v10 offset:38080
	s_waitcnt lgkmcnt(6)
	v_pk_mul_f32 v[92:93], v[92:93], v[208:209]
	v_pk_mul_f32 v[94:95], v[94:95], v[210:211]
	s_nop 1
	v_mfma_f32_16x16x32_bf16 v[92:95], v[204:207], v[200:203], v[92:95]
	ds_read_b128 v[152:155], v9 offset:22528
	ds_read_b128 v[172:175], v10 offset:38144
	s_waitcnt lgkmcnt(6)
	v_pk_mul_f32 v[96:97], v[96:97], v[216:217]
	v_pk_mul_f32 v[98:99], v[98:99], v[218:219]
	s_nop 1
	v_mfma_f32_16x16x32_bf16 v[96:99], v[212:215], v[200:203], v[96:99]
	ds_read_b128 v[176:179], v9 offset:23808
	ds_read_b128 v[180:183], v10 offset:38208
	s_waitcnt lgkmcnt(6)
	v_pk_mul_f32 v[100:101], v[100:101], v[224:225]
	v_pk_mul_f32 v[102:103], v[102:103], v[226:227]
	s_nop 1
	v_mfma_f32_16x16x32_bf16 v[100:103], v[220:223], v[200:203], v[100:103]
	ds_read_b128 v[184:187], v9 offset:25088
	ds_read_b128 v[188:191], v10 offset:38272
	s_waitcnt lgkmcnt(6)
	v_pk_mul_f32 v[104:105], v[104:105], v[144:145]
	v_pk_mul_f32 v[106:107], v[106:107], v[146:147]
	s_nop 1
	v_mfma_f32_16x16x32_bf16 v[104:107], v[228:231], v[200:203], v[104:107]
	ds_read_b128 v[204:207], v9 offset:26368
	ds_read_b128 v[208:211], v10 offset:38336
	s_waitcnt lgkmcnt(6)
	v_pk_mul_f32 v[108:109], v[108:109], v[172:173]
	v_pk_mul_f32 v[110:111], v[110:111], v[174:175]
	s_nop 1
	v_mfma_f32_16x16x32_bf16 v[108:111], v[152:155], v[200:203], v[108:111]
	s_waitcnt lgkmcnt(4)
	v_pk_mul_f32 v[112:113], v[112:113], v[180:181]
	v_pk_mul_f32 v[114:115], v[114:115], v[182:183]
	s_nop 1
	v_mfma_f32_16x16x32_bf16 v[112:115], v[176:179], v[200:203], v[112:115]
	s_waitcnt lgkmcnt(2)
	v_pk_mul_f32 v[116:117], v[116:117], v[188:189]
	v_pk_mul_f32 v[118:119], v[118:119], v[190:191]
	s_nop 1
	v_mfma_f32_16x16x32_bf16 v[116:119], v[184:187], v[200:203], v[116:119]
	s_waitcnt lgkmcnt(0)
	v_pk_mul_f32 v[120:121], v[120:121], v[208:209]
	v_pk_mul_f32 v[122:123], v[122:123], v[210:211]
	s_nop 1
	v_mfma_f32_16x16x32_bf16 v[120:123], v[204:207], v[200:203], v[120:123]
	ds_write_b32 v11, v136
	ds_write_b32 v11, v140 offset:8448
	ds_write_b32 v11, v137 offset:528
	ds_write_b32 v11, v141 offset:8976
	ds_write_b32 v11, v138 offset:1056
	ds_write_b32 v11, v142 offset:9504
	ds_write_b32 v11, v139 offset:1584
	ds_write_b32 v11, v143 offset:10032
.Lhg_joined_5:
	s_cmp_gt_u32 s28, 29
	s_cbranch_scc1 .Lhg_nop1_14
	s_cmp_gt_u32 s28, 28
	s_cbranch_scc1 .Lhg_wl29_15
	s_waitcnt vmcnt(57)
	s_branch .Lhg_wlj_16

.Lhg_wlj_16:
	v_mov_b32_e32 v28, v76
	v_mov_b32_e32 v29, v77
	v_mov_b32_e32 v30, v78
	v_mov_b32_e32 v31, v79
	v_mov_b32_e32 v32, v80
	v_mov_b32_e32 v33, v81
	v_mov_b32_e32 v34, v82
	v_mov_b32_e32 v35, v83
	v_add_f32_e32 v200, v28, v29
	v_add_f32_e32 v200, v200, v30
	v_add_f32_e32 v200, v200, v31
	v_add_f32_e32 v200, v200, v32
	v_add_f32_e32 v200, v200, v33
	v_add_f32_e32 v200, v200, v34
	v_add_f32_e32 v200, v200, v35
	ds_write_b32 v1, v200
.Lhg_nop1_14:
	s_waitcnt lgkmcnt(0)
	s_barrier
	ds_read_b128 v[200:203], v12
	ds_read_b128 v[204:207], v12 offset:16
	s_waitcnt lgkmcnt(0)
	v_cvt_pk_bf16_f32 v200, v200, v201
	v_cvt_pk_bf16_f32 v201, v202, v203
	v_cvt_pk_bf16_f32 v202, v204, v205
	v_cvt_pk_bf16_f32 v203, v206, v207
	global_store_dwordx4 v13, v[200:203], s[14:15]
	s_add_u32 s14, s14, 0x10000
	s_addc_u32 s15, s15, 0
	v_xor_b32_e32 v2, 0x10000, v2
	v_xor_b32_e32 v4, 0x10000, v4
	v_xor_b32_e32 v26, 0x10000, v26
	v_xor_b32_e32 v5, 0x10000, v5
	v_xor_b32_e32 v6, 0x10000, v6
	v_xor_b32_e32 v7, 0x10000, v7
	v_xor_b32_e32 v8, 0x10000, v8
	v_xor_b32_e32 v9, 0x10000, v9
	v_xor_b32_e32 v10, 0x10000, v10
	v_xor_b32_e32 v11, 0x10000, v11
	v_xor_b32_e32 v12, 0x10000, v12
	s_add_i32 s28, s28, 1
	s_cmp_eq_u32 s28, 31
	s_cbranch_scc1 .Lhg_last
	s_cmp_gt_u32 s28, 28
	s_cbranch_scc1 .Lhg_nolf_17
	global_load_dword v76, v14, s[4:5]
	global_load_dword v77, v14, s[4:5] offset:3072
	global_load_dword v78, v15, s[4:5]
	global_load_dword v79, v15, s[4:5] offset:3072
	global_load_dword v80, v16, s[4:5]
	global_load_dword v81, v16, s[4:5] offset:3072
	global_load_dword v82, v17, s[4:5]
	global_load_dword v83, v17, s[4:5] offset:3072
	s_add_u32 s4, s4, 0x18000
	s_addc_u32 s5, s5, 0
.Lhg_nolf_17:
	s_cmp_gt_u32 s28, 29
	s_cbranch_scc1 .Lhg_noqv_18
	global_load_ushort v60, v18, s[8:9]
	global_load_ushort v61, v18, s[8:9] offset:1536
	global_load_ushort v62, v18, s[8:9] offset:3072
	global_load_ushort v63, v19, s[8:9]
	global_load_ushort v64, v19, s[8:9] offset:1536
	global_load_ushort v65, v19, s[8:9] offset:3072
	global_load_ushort v66, v20, s[8:9]
	global_load_ushort v67, v20, s[8:9] offset:1536
	global_load_ushort v68, v18, s[10:11]
	global_load_ushort v69, v18, s[10:11] offset:1536
	global_load_ushort v70, v18, s[10:11] offset:3072
	global_load_ushort v71, v19, s[10:11]
	global_load_ushort v72, v19, s[10:11] offset:1536
	global_load_ushort v73, v19, s[10:11] offset:3072
	global_load_ushort v74, v20, s[10:11]
	global_load_ushort v75, v20, s[10:11] offset:1536
	s_add_u32 s8, s8, 0xc000
	s_addc_u32 s9, s9, 0
	s_add_u32 s10, s10, 0xc000
	s_addc_u32 s11, s11, 0

.Lhg_wqj_23:
	ds_read_b32 v200, v0 offset:55296
	ds_read_b32 v201, v0 offset:55808
	ds_read_b32 v202, v0 offset:56320
	ds_read_b32 v203, v0 offset:56832
	v_lshl_or_b32 v220, v45, 16, v44
	v_lshl_or_b32 v221, v47, 16, v46
	v_lshl_or_b32 v222, v49, 16, v48
	v_lshl_or_b32 v223, v51, 16, v50
	ds_write_b128 v4, v[220:223] offset:27648
	s_waitcnt lgkmcnt(1)
	v_mul_f32_e32 v204, v21, v200
	v_fmac_f32_e32 v204, v22, v201
	v_fmac_f32_e32 v204, v23, v202
	v_add_f32_e32 v205, v200, v201
	v_add_f32_e32 v205, v205, v202
	v_add_f32_e32 v205, v205, v203
	v_mov_b32_e32 v219, v28
	v_add_f32_e32 v218, v204, v219
	v_mul_f32_e32 v207, 0x3fb8aa3b, v28
	v_exp_f32_e32 v207, v207
	v_lshlrev_b32_e32 v209, 16, v36
	v_sub_f32_e32 v208, 1.0, v207
	v_mul_f32_e32 v207, 0x3fb8aa3b, v218
	v_exp_f32_e32 v207, v207
	v_add_f32_e32 v206, v218, v24
	v_mul_f32_e32 v224, v209, v207
	v_mul_f32_e32 v206, 0x3fb8aa3b, v206
	v_exp_f32_e32 v206, v206
	v_sub_f32_e32 v207, v205, v218
	v_mul_f32_e32 v28, v209, v206
	v_mul_f32_e32 v207, 0x3fb8aa3b, v207
	v_exp_f32_e32 v207, v207
	v_min_f32_e64 v206, -v218, s29
	v_mul_f32_e32 v210, v208, v207
	v_mul_f32_e32 v206, 0x3fb8aa3b, v206
	v_exp_f32_e32 v206, v206
	s_nop 0
	v_mul_f32_e32 v232, v208, v206
	v_add_f32_e32 v219, v219, v29
	v_add_f32_e32 v218, v204, v219
	v_mul_f32_e32 v207, 0x3fb8aa3b, v29
	v_exp_f32_e32 v207, v207
	v_lshlrev_b32_e32 v209, 16, v37
	v_sub_f32_e32 v208, 1.0, v207
	v_mul_f32_e32 v207, 0x3fb8aa3b, v218
	v_exp_f32_e32 v207, v207
	v_add_f32_e32 v206, v218, v24
	v_mul_f32_e32 v225, v209, v207
	v_mul_f32_e32 v206, 0x3fb8aa3b, v206
	v_exp_f32_e32 v206, v206
	v_sub_f32_e32 v207, v205, v218
	v_mul_f32_e32 v29, v209, v206
	v_mul_f32_e32 v207, 0x3fb8aa3b, v207
	v_exp_f32_e32 v207, v207
	v_min_f32_e64 v206, -v218, s29
	v_mul_f32_e32 v211, v208, v207
	v_mul_f32_e32 v206, 0x3fb8aa3b, v206
	v_exp_f32_e32 v206, v206
	s_nop 0
	v_mul_f32_e32 v233, v208, v206
	v_add_f32_e32 v219, v219, v30
	v_add_f32_e32 v218, v204, v219
	v_mul_f32_e32 v207, 0x3fb8aa3b, v30
	v_exp_f32_e32 v207, v207
	v_lshlrev_b32_e32 v209, 16, v38
	v_sub_f32_e32 v208, 1.0, v207
	v_mul_f32_e32 v207, 0x3fb8aa3b, v218
	v_exp_f32_e32 v207, v207
	v_add_f32_e32 v206, v218, v24
	v_mul_f32_e32 v226, v209, v207
	v_mul_f32_e32 v206, 0x3fb8aa3b, v206
	v_exp_f32_e32 v206, v206
	v_sub_f32_e32 v207, v205, v218
	v_mul_f32_e32 v30, v209, v206
	v_mul_f32_e32 v207, 0x3fb8aa3b, v207
	v_exp_f32_e32 v207, v207
	v_min_f32_e64 v206, -v218, s29
	v_mul_f32_e32 v212, v208, v207
	v_mul_f32_e32 v206, 0x3fb8aa3b, v206
	v_exp_f32_e32 v206, v206
	s_nop 0
	v_mul_f32_e32 v234, v208, v206
	v_add_f32_e32 v219, v219, v31
	v_add_f32_e32 v218, v204, v219
	v_mul_f32_e32 v207, 0x3fb8aa3b, v31
	v_exp_f32_e32 v207, v207
	v_lshlrev_b32_e32 v209, 16, v39
	v_sub_f32_e32 v208, 1.0, v207
	v_mul_f32_e32 v207, 0x3fb8aa3b, v218
	v_exp_f32_e32 v207, v207
	v_add_f32_e32 v206, v218, v24
	v_mul_f32_e32 v227, v209, v207
	v_mul_f32_e32 v206, 0x3fb8aa3b, v206
	v_exp_f32_e32 v206, v206
	v_sub_f32_e32 v207, v205, v218
	v_mul_f32_e32 v31, v209, v206
	v_mul_f32_e32 v207, 0x3fb8aa3b, v207
	v_exp_f32_e32 v207, v207
	v_min_f32_e64 v206, -v218, s29
	v_mul_f32_e32 v213, v208, v207
	v_mul_f32_e32 v206, 0x3fb8aa3b, v206
	v_exp_f32_e32 v206, v206
	s_nop 0
	v_mul_f32_e32 v235, v208, v206
	v_add_f32_e32 v219, v219, v32
	v_add_f32_e32 v218, v204, v219
	v_mul_f32_e32 v207, 0x3fb8aa3b, v32
	v_exp_f32_e32 v207, v207
	v_lshlrev_b32_e32 v209, 16, v40
	v_sub_f32_e32 v208, 1.0, v207
	v_mul_f32_e32 v207, 0x3fb8aa3b, v218
	v_exp_f32_e32 v207, v207
	v_add_f32_e32 v206, v218, v24
	v_mul_f32_e32 v228, v209, v207
	v_mul_f32_e32 v206, 0x3fb8aa3b, v206
	v_exp_f32_e32 v206, v206
	v_sub_f32_e32 v207, v205, v218
	v_mul_f32_e32 v32, v209, v206
	v_mul_f32_e32 v207, 0x3fb8aa3b, v207
	v_exp_f32_e32 v207, v207
	v_min_f32_e64 v206, -v218, s29
	v_mul_f32_e32 v214, v208, v207
	v_mul_f32_e32 v206, 0x3fb8aa3b, v206
	v_exp_f32_e32 v206, v206
	s_nop 0
	v_mul_f32_e32 v236, v208, v206
	v_add_f32_e32 v219, v219, v33
	v_add_f32_e32 v218, v204, v219
	v_mul_f32_e32 v207, 0x3fb8aa3b, v33
	v_exp_f32_e32 v207, v207
	v_lshlrev_b32_e32 v209, 16, v41
	v_sub_f32_e32 v208, 1.0, v207
	v_mul_f32_e32 v207, 0x3fb8aa3b, v218
	v_exp_f32_e32 v207, v207
	v_add_f32_e32 v206, v218, v24
	v_mul_f32_e32 v229, v209, v207
	v_mul_f32_e32 v206, 0x3fb8aa3b, v206
	v_exp_f32_e32 v206, v206
	v_sub_f32_e32 v207, v205, v218
	v_mul_f32_e32 v33, v209, v206
	v_mul_f32_e32 v207, 0x3fb8aa3b, v207
	v_exp_f32_e32 v207, v207
	v_min_f32_e64 v206, -v218, s29
	v_mul_f32_e32 v215, v208, v207
	v_mul_f32_e32 v206, 0x3fb8aa3b, v206
	v_exp_f32_e32 v206, v206
	s_nop 0
	v_mul_f32_e32 v237, v208, v206
	v_add_f32_e32 v219, v219, v34
	v_add_f32_e32 v218, v204, v219
	v_mul_f32_e32 v207, 0x3fb8aa3b, v34
	v_exp_f32_e32 v207, v207
	v_lshlrev_b32_e32 v209, 16, v42
	v_sub_f32_e32 v208, 1.0, v207
	v_mul_f32_e32 v207, 0x3fb8aa3b, v218
	v_exp_f32_e32 v207, v207
	v_add_f32_e32 v206, v218, v24
	v_mul_f32_e32 v230, v209, v207
	v_mul_f32_e32 v206, 0x3fb8aa3b, v206
	v_exp_f32_e32 v206, v206
	v_sub_f32_e32 v207, v205, v218
	v_mul_f32_e32 v34, v209, v206
	v_mul_f32_e32 v207, 0x3fb8aa3b, v207
	v_exp_f32_e32 v207, v207
	v_min_f32_e64 v206, -v218, s29
	v_mul_f32_e32 v216, v208, v207
	v_mul_f32_e32 v206, 0x3fb8aa3b, v206
	v_exp_f32_e32 v206, v206
	s_nop 0
	v_mul_f32_e32 v238, v208, v206
	v_add_f32_e32 v219, v219, v35
	v_add_f32_e32 v218, v204, v219
	v_mul_f32_e32 v207, 0x3fb8aa3b, v35
	v_exp_f32_e32 v207, v207
	v_lshlrev_b32_e32 v209, 16, v43
	v_sub_f32_e32 v208, 1.0, v207
	v_mul_f32_e32 v207, 0x3fb8aa3b, v218
	v_exp_f32_e32 v207, v207
	v_add_f32_e32 v206, v218, v24
	v_mul_f32_e32 v231, v209, v207
	v_mul_f32_e32 v206, 0x3fb8aa3b, v206
	v_exp_f32_e32 v206, v206
	v_sub_f32_e32 v207, v205, v218
	v_mul_f32_e32 v35, v209, v206
	v_mul_f32_e32 v207, 0x3fb8aa3b, v207
	v_exp_f32_e32 v207, v207
	v_min_f32_e64 v206, -v218, s29
	v_mul_f32_e32 v217, v208, v207
	v_mul_f32_e32 v206, 0x3fb8aa3b, v206
	v_exp_f32_e32 v206, v206
	s_nop 0
	v_mul_f32_e32 v239, v208, v206
	v_cvt_pk_bf16_f32 v224, v224, v225
	ds_write_b16 v2, v224
	ds_write_b16_d16_hi v2, v224 offset:272
	v_cvt_pk_bf16_f32 v232, v232, v233
	ds_write_b16 v2, v232 offset:8704
	ds_write_b16_d16_hi v2, v232 offset:8976
	v_cvt_pk_bf16_f32 v226, v226, v227
	ds_write_b16 v2, v226 offset:544
	ds_write_b16_d16_hi v2, v226 offset:816
	v_cvt_pk_bf16_f32 v234, v234, v235
	ds_write_b16 v2, v234 offset:9248
	ds_write_b16_d16_hi v2, v234 offset:9520
	v_cvt_pk_bf16_f32 v228, v228, v229
	ds_write_b16 v2, v228 offset:1088
	ds_write_b16_d16_hi v2, v228 offset:1360
	v_cvt_pk_bf16_f32 v236, v236, v237
	ds_write_b16 v2, v236 offset:9792
	ds_write_b16_d16_hi v2, v236 offset:10064
	v_cvt_pk_bf16_f32 v230, v230, v231
	ds_write_b16 v2, v230 offset:1632
	ds_write_b16_d16_hi v2, v230 offset:1904
	v_cvt_pk_bf16_f32 v238, v238, v239
	ds_write_b16 v2, v238 offset:10336
	ds_write_b16_d16_hi v2, v238 offset:10608
	v_cvt_pk_bf16_f32 v210, v210, v211
	v_cvt_pk_bf16_f32 v211, v212, v213
	v_cvt_pk_bf16_f32 v212, v214, v215
	v_cvt_pk_bf16_f32 v213, v216, v217
	ds_write_b128 v4, v[210:213] offset:17408
	v_cvt_pk_bf16_f32 v28, v28, v29
	v_cvt_pk_bf16_f32 v30, v30, v31
	v_cvt_pk_bf16_f32 v32, v32, v33
	v_cvt_pk_bf16_f32 v34, v34, v35
	global_store_short v18, v28, s[12:13]
	global_store_short_d16_hi v18, v28, s[12:13] offset:1536
	global_store_short v18, v30, s[12:13] offset:3072
	global_store_short_d16_hi v19, v30, s[12:13]
	global_store_short v19, v32, s[12:13] offset:1536
	global_store_short_d16_hi v19, v32, s[12:13] offset:3072
	global_store_short v20, v34, s[12:13]
	global_store_short_d16_hi v20, v34, s[12:13] offset:1536
	s_add_u32 s12, s12, 0xc000
	s_addc_u32 s13, s13, 0
	s_cmp_gt_u32 s18, 1
	s_cbranch_scc1 .Lhg_w01_24
	v_mul_f32_e32 v207, 0x3fb8aa3b, v205
	v_exp_f32_e32 v207, v207
	s_nop 0
	ds_write_b32 v26, v207 offset:37888

.Lhg_wlj_31:
	v_mov_b32_e32 v52, v84
	v_mov_b32_e32 v53, v85
	v_mov_b32_e32 v54, v86
	v_mov_b32_e32 v55, v87
	v_mov_b32_e32 v56, v88
	v_mov_b32_e32 v57, v89
	v_mov_b32_e32 v58, v90
	v_mov_b32_e32 v59, v91
	v_add_f32_e32 v200, v52, v53
	v_add_f32_e32 v200, v200, v54
	v_add_f32_e32 v200, v200, v55
	v_add_f32_e32 v200, v200, v56
	v_add_f32_e32 v200, v200, v57
	v_add_f32_e32 v200, v200, v58
	v_add_f32_e32 v200, v200, v59
	ds_write_b32 v1, v200 offset:2048

.Lhg_last:
	ds_read_b128 v[144:147], v5 offset:8704
	ds_read_b128 v[148:151], v5 offset:13056
	ds_read_b128 v[152:155], v5 offset:0
	ds_read_b128 v[172:175], v5 offset:4352
	ds_read_b128 v[176:179], v5 offset:8768
	ds_read_b128 v[180:183], v5 offset:13120
	ds_read_b128 v[184:187], v5 offset:64
	ds_read_b128 v[188:191], v5 offset:4416
	ds_read_b128 v[200:203], v5 offset:8832
	ds_read_b128 v[204:207], v5 offset:13184
	ds_read_b128 v[208:211], v5 offset:128
	ds_read_b128 v[212:215], v5 offset:4480
	s_waitcnt lgkmcnt(8)
	v_mfma_f32_16x16x32_bf16 v[124:127], v[144:147], v[152:155], 0
	v_mfma_f32_16x16x32_bf16 v[128:131], v[144:147], v[172:175], 0
	v_mfma_f32_16x16x32_bf16 v[132:135], v[148:151], v[172:175], 0
	ds_read_b128 v[216:219], v5 offset:8896
	ds_read_b128 v[220:223], v5 offset:13248
	ds_read_b128 v[224:227], v5 offset:192
	ds_read_b128 v[228:231], v5 offset:4544
	s_waitcnt lgkmcnt(8)
	v_mfma_f32_16x16x32_bf16 v[124:127], v[176:179], v[184:187], v[124:127]
	v_mfma_f32_16x16x32_bf16 v[128:131], v[176:179], v[188:191], v[128:131]
	v_mfma_f32_16x16x32_bf16 v[132:135], v[180:183], v[188:191], v[132:135]
	ds_read_b64 v[144:145], v6 offset:0
	ds_read_b64 v[146:147], v6 offset:32
	ds_read_b64 v[148:149], v6 offset:4352
	ds_read_b64 v[150:151], v6 offset:4384
	s_waitcnt lgkmcnt(8)
	v_mfma_f32_16x16x32_bf16 v[124:127], v[200:203], v[208:211], v[124:127]
	v_mfma_f32_16x16x32_bf16 v[128:131], v[200:203], v[212:215], v[128:131]
	v_mfma_f32_16x16x32_bf16 v[132:135], v[204:207], v[212:215], v[132:135]
	ds_read_b64 v[152:153], v6 offset:64
	ds_read_b64 v[154:155], v6 offset:96
	ds_read_b64 v[172:173], v6 offset:4416
	ds_read_b64 v[174:175], v6 offset:4448
	s_waitcnt lgkmcnt(8)
	v_mfma_f32_16x16x32_bf16 v[124:127], v[216:219], v[224:227], v[124:127]
	v_mfma_f32_16x16x32_bf16 v[128:131], v[216:219], v[228:231], v[128:131]
	v_mfma_f32_16x16x32_bf16 v[132:135], v[220:223], v[228:231], v[132:135]
	ds_read_b64 v[176:177], v6 offset:128
	ds_read_b64 v[178:179], v6 offset:160
	ds_read_b64 v[180:181], v6 offset:4480
	ds_read_b64 v[182:183], v6 offset:4512
	v_cvt_pk_bf16_f32 v232, v92, v93
	v_cvt_pk_bf16_f32 v233, v94, v95
	v_cvt_pk_bf16_f32 v234, v96, v97
	v_cvt_pk_bf16_f32 v235, v98, v99
	s_waitcnt lgkmcnt(8)
	s_nop 1
	v_mfma_f32_16x16x32_bf16 v[136:139], v[144:147], v[232:235], 0
	v_mfma_f32_16x16x32_bf16 v[140:143], v[148:151], v[232:235], 0
	ds_read_b64 v[184:185], v6 offset:192
	ds_read_b64 v[186:187], v6 offset:224
	ds_read_b64 v[188:189], v6 offset:4544
	ds_read_b64 v[190:191], v6 offset:4576
	v_cvt_pk_bf16_f32 v232, v100, v101
	v_cvt_pk_bf16_f32 v233, v102, v103
	v_cvt_pk_bf16_f32 v234, v104, v105
	v_cvt_pk_bf16_f32 v235, v106, v107
	s_waitcnt lgkmcnt(8)
	s_nop 1
	v_mfma_f32_16x16x32_bf16 v[136:139], v[152:155], v[232:235], v[136:139]
	v_mfma_f32_16x16x32_bf16 v[140:143], v[172:175], v[232:235], v[140:143]
	ds_read_b64 v[236:237], v7 offset:27648
	ds_read_b64 v[238:239], v7 offset:27680
	ds_read_b128 v[200:203], v8 offset:27648
	v_cvt_pk_bf16_f32 v232, v108, v109
	v_cvt_pk_bf16_f32 v233, v110, v111
	v_cvt_pk_bf16_f32 v234, v112, v113
	v_cvt_pk_bf16_f32 v235, v114, v115
	s_waitcnt lgkmcnt(7)
	s_nop 1
	v_mfma_f32_16x16x32_bf16 v[136:139], v[176:179], v[232:235], v[136:139]
	v_mfma_f32_16x16x32_bf16 v[140:143], v[180:183], v[232:235], v[140:143]
	ds_read_b128 v[204:207], v9 offset:17408
	ds_read_b128 v[208:211], v10 offset:37888
	v_cvt_pk_bf16_f32 v232, v116, v117
	v_cvt_pk_bf16_f32 v233, v118, v119
	v_cvt_pk_bf16_f32 v234, v120, v121
	v_cvt_pk_bf16_f32 v235, v122, v123
	s_waitcnt lgkmcnt(5)
	s_nop 1
	v_mfma_f32_16x16x32_bf16 v[136:139], v[184:187], v[232:235], v[136:139]
	v_mfma_f32_16x16x32_bf16 v[140:143], v[188:191], v[232:235], v[140:143]
	ds_read_b128 v[212:215], v9 offset:18688
	ds_read_b128 v[216:219], v10 offset:37952
	v_cndmask_b32_e64 v124, 0, v124, s[40:41]
	v_cndmask_b32_e64 v132, 0, v132, s[40:41]
	v_cndmask_b32_e64 v125, 0, v125, s[42:43]
	v_cndmask_b32_e64 v133, 0, v133, s[42:43]
	v_cndmask_b32_e64 v126, 0, v126, s[44:45]
	v_cndmask_b32_e64 v134, 0, v134, s[44:45]
	v_cndmask_b32_e64 v127, 0, v127, s[46:47]
	v_cndmask_b32_e64 v135, 0, v135, s[46:47]
	v_cvt_pk_bf16_f32 v124, v124, v125
	v_cvt_pk_bf16_f32 v125, v126, v127
	v_mov_b32_e32 v126, 0
	v_mov_b32_e32 v127, 0
	v_cvt_pk_bf16_f32 v128, v128, v129
	v_cvt_pk_bf16_f32 v129, v130, v131
	v_cvt_pk_bf16_f32 v130, v132, v133
	v_cvt_pk_bf16_f32 v131, v134, v135
	s_waitcnt lgkmcnt(4)
	s_nop 1
	v_mfma_f32_16x16x32_bf16 v[136:139], v[124:127], v[236:239], v[136:139]
	v_mfma_f32_16x16x32_bf16 v[140:143], v[128:131], v[236:239], v[140:143]
	ds_read_b128 v[220:223], v9 offset:19968
	ds_read_b128 v[224:227], v10 offset:38016
	ds_read_b128 v[228:231], v9 offset:21248
	ds_read_b128 v[144:147], v10 offset:38080
	s_waitcnt lgkmcnt(6)
	v_pk_mul_f32 v[92:93], v[92:93], v[208:209]
	v_pk_mul_f32 v[94:95], v[94:95], v[210:211]
	s_nop 1
	v_mfma_f32_16x16x32_bf16 v[92:95], v[204:207], v[200:203], v[92:95]
	ds_read_b128 v[152:155], v9 offset:22528
	ds_read_b128 v[172:175], v10 offset:38144
	s_waitcnt lgkmcnt(6)
	v_pk_mul_f32 v[96:97], v[96:97], v[216:217]
	v_pk_mul_f32 v[98:99], v[98:99], v[218:219]
	s_nop 1
	v_mfma_f32_16x16x32_bf16 v[96:99], v[212:215], v[200:203], v[96:99]
	ds_read_b128 v[176:179], v9 offset:23808
	ds_read_b128 v[180:183], v10 offset:38208
	s_waitcnt lgkmcnt(6)
	v_pk_mul_f32 v[100:101], v[100:101], v[224:225]
	v_pk_mul_f32 v[102:103], v[102:103], v[226:227]
	s_nop 1
	v_mfma_f32_16x16x32_bf16 v[100:103], v[220:223], v[200:203], v[100:103]
	ds_read_b128 v[184:187], v9 offset:25088
	ds_read_b128 v[188:191], v10 offset:38272
	s_waitcnt lgkmcnt(6)
	v_pk_mul_f32 v[104:105], v[104:105], v[144:145]
	v_pk_mul_f32 v[106:107], v[106:107], v[146:147]
	s_nop 1
	v_mfma_f32_16x16x32_bf16 v[104:107], v[228:231], v[200:203], v[104:107]
	ds_read_b128 v[204:207], v9 offset:26368
	ds_read_b128 v[208:211], v10 offset:38336
	s_waitcnt lgkmcnt(6)
	v_pk_mul_f32 v[108:109], v[108:109], v[172:173]
	v_pk_mul_f32 v[110:111], v[110:111], v[174:175]
	s_nop 1
	v_mfma_f32_16x16x32_bf16 v[108:111], v[152:155], v[200:203], v[108:111]
	s_waitcnt lgkmcnt(4)
	v_pk_mul_f32 v[112:113], v[112:113], v[180:181]
	v_pk_mul_f32 v[114:115], v[114:115], v[182:183]
	s_nop 1
	v_mfma_f32_16x16x32_bf16 v[112:115], v[176:179], v[200:203], v[112:115]
	s_waitcnt lgkmcnt(2)
	v_pk_mul_f32 v[116:117], v[116:117], v[188:189]
	v_pk_mul_f32 v[118:119], v[118:119], v[190:191]
	s_nop 1
	v_mfma_f32_16x16x32_bf16 v[116:119], v[184:187], v[200:203], v[116:119]
	s_waitcnt lgkmcnt(0)
	v_pk_mul_f32 v[120:121], v[120:121], v[208:209]
	v_pk_mul_f32 v[122:123], v[122:123], v[210:211]
	s_nop 1
	v_mfma_f32_16x16x32_bf16 v[120:123], v[204:207], v[200:203], v[120:123]
	ds_write_b32 v11, v136
	ds_write_b32 v11, v140 offset:8448
	ds_write_b32 v11, v137 offset:528
	ds_write_b32 v11, v141 offset:8976
	ds_write_b32 v11, v138 offset:1056
	ds_write_b32 v11, v142 offset:9504
	ds_write_b32 v11, v139 offset:1584
	ds_write_b32 v11, v143 offset:10032
	s_waitcnt lgkmcnt(0)
	s_barrier
	ds_read_b128 v[200:203], v12
	ds_read_b128 v[204:207], v12 offset:16
	s_waitcnt lgkmcnt(0)
	v_cvt_pk_bf16_f32 v200, v200, v201
	v_cvt_pk_bf16_f32 v201, v202, v203
	v_cvt_pk_bf16_f32 v202, v204, v205
	v_cvt_pk_bf16_f32 v203, v206, v207
	global_store_dwordx4 v13, v[200:203], s[14:15]
	s_add_u32 s14, s14, 0x10000
	s_addc_u32 s15, s15, 0
	s_lshl_b32 s0, s2, 16
	s_add_u32 s4, s6, s0
	s_addc_u32 s5, s7, 0
	s_add_u32 s4, s4, 0x4200000
	s_addc_u32 s5, s5, 0
	global_store_dword v25, v92, s[4:5] offset:0
	global_store_dword v25, v93, s[4:5] offset:512
	global_store_dword v25, v94, s[4:5] offset:1024
	global_store_dword v25, v95, s[4:5] offset:1536
	v_add_u32_e32 v25, 0x2000, v25
	global_store_dword v25, v96, s[4:5] offset:0
	global_store_dword v25, v97, s[4:5] offset:512
	global_store_dword v25, v98, s[4:5] offset:1024
	global_store_dword v25, v99, s[4:5] offset:1536
	v_add_u32_e32 v25, 0x2000, v25
	global_store_dword v25, v100, s[4:5] offset:0
	global_store_dword v25, v101, s[4:5] offset:512
	global_store_dword v25, v102, s[4:5] offset:1024
	global_store_dword v25, v103, s[4:5] offset:1536
	v_add_u32_e32 v25, 0x2000, v25
	global_store_dword v25, v104, s[4:5] offset:0
	global_store_dword v25, v105, s[4:5] offset:512
	global_store_dword v25, v106, s[4:5] offset:1024
	global_store_dword v25, v107, s[4:5] offset:1536
	v_add_u32_e32 v25, 0x2000, v25
	global_store_dword v25, v108, s[4:5] offset:0
	global_store_dword v25, v109, s[4:5] offset:512
	global_store_dword v25, v110, s[4:5] offset:1024
	global_store_dword v25, v111, s[4:5] offset:1536
	v_add_u32_e32 v25, 0x2000, v25
	global_store_dword v25, v112, s[4:5] offset:0
	global_store_dword v25, v113, s[4:5] offset:512
	global_store_dword v25, v114, s[4:5] offset:1024
	global_store_dword v25, v115, s[4:5] offset:1536
	v_add_u32_e32 v25, 0x2000, v25
	global_store_dword v25, v116, s[4:5] offset:0
	global_store_dword v25, v117, s[4:5] offset:512
	global_store_dword v25, v118, s[4:5] offset:1024
	global_store_dword v25, v119, s[4:5] offset:1536
	v_add_u32_e32 v25, 0x2000, v25
	global_store_dword v25, v120, s[4:5] offset:0
	global_store_dword v25, v121, s[4:5] offset:512
	global_store_dword v25, v122, s[4:5] offset:1024
	global_store_dword v25, v123, s[4:5] offset:1536
	s_cmp_gt_u32 s18, 1
	s_cbranch_scc1 .Lhg_done
	v_mul_f32_e32 v200, 0x3fb8aa3b, v24
	v_exp_f32_e32 v200, v200
	s_lshl_b32 s0, s2, 9
	s_add_u32 s4, s6, s0
	s_addc_u32 s5, s7, 0
	s_add_u32 s4, s4, 0x5200000
	s_addc_u32 s5, s5, 0
	global_store_dword v0, v200, s[4:5]
